# speedup vs baseline: 1.0543x; 1.0090x over previous
; DEV int otid() { int t = threadIdx.x; asm volatile("" : "+v"(t)); return t; }
; template <bool SWAP, class RowA, class Epi>
; DEV void gemm_tile(unsigned char* smem, RowA rowA, const bf16_t* Bt, int K, Epi epi) {
;   const int tid = otid(), lane = tid & 63, wid = tid >> 6, wr = wid >> 1, wc = wid & 1, fr = lane & 15, fq = lane >> 4;
;   const int r0 = tid >> 2;
;   const int a_w = (r0 >> 2) & 3, g_w = (((a_w ^ (a_w >> 1)) & 1) << 1) | (a_w >> 1);
;   const int cc = ((tid & 3) ^ g_w) * 8;
;   const int a_r = (fr >> 2) & 3, g_r = (((a_r ^ (a_r >> 1)) & 1) << 1) | (a_r >> 1);
;   const int rdoff = fr * 64 + ((fq ^ g_r) * 16);
;   const bf16_t* a0 = rowA(r0) + cc;
;   const bf16_t* a1 = rowA(r0 + 64) + cc;
;   const bf16_t* b0 = Bt + (size_t)r0 * K + cc;
;   const bf16_t* b1 = Bt + (size_t)(r0 + 64) * K + cc;
;   f32x4 acc[4][4];
; #pragma unroll
;   for (int m = 0; m < 4; ++m)
; #pragma unroll
;     for (int n = 0; n < 4; ++n) acc[m][n] = f32x4{0.f, 0.f, 0.f, 0.f};
;   const int nk = K / 32;
;   auto stage = [&](int kt, int buf) {
;     unsigned char* SA = smem + buf * 16384 + tid * 16;
;     unsigned char* SB = SA + 8192;
;     const int ko = kt * 32;
;     glds16(a0 + ko, SA); glds16(a1 + ko, SA + 4096);
;     glds16(b0 + ko, SB); glds16(b1 + ko, SB + 4096);
;   };
;   stage(0, 0);
; DEV void phase_moe2(const Params& p, int l, unsigned char* smem) {
;     ...
;   for (int t = blockIdx.x; t < ntile; t += gridDim.x) {
;     int e = 0;
;     while (s_tile[e + 1] <= t) ++e;
;     const int local = t - s_tile[e], cnt = s_cnt[e], nmt = (cnt + 127) >> 7;
;     const int mt = local / NTN_, nt = local % NTN_;
;     const int rowoff = s_off[e];
;     const float* bd = p.b_dn + (size_t)(l * 32 + e) * 1024;
;     const float* gl = p.glist + e * NTOK;
;     const bf16_t* A = p.act + (size_t)(rowoff + mt * 128) * 1024;
;     gemm_tile<true>(smem, [&](int r) { return A + (size_t)r * 1024; },
;       p.wdn_t + ((size_t)(l * 32 + e) * 1024 + nt * 128) * 1024, 1024,
.LBB0_2409:
	v_mov_b32_e32 v0, s0
	ds_read_b32 v0, v0 offset:33032
	s_add_i32 s8, s8, 1
	s_add_i32 s0, s0, 4
	s_add_u32 s6, s6, 0x200000
	s_addc_u32 s7, s7, 0
	s_waitcnt lgkmcnt(0)
	v_cmp_ge_i32_e32 vcc, s22, v0
	s_cbranch_vccnz .LBB0_2409
	v_mov_b32_e32 v0, s0
	ds_read_b32 v1, v0 offset:33024
	v_add_u32_e32 v0, 0x8000, v0
	v_mov_b32_e32 v12, v122
	ds_read2_b32 v[74:75], v0 offset1:32
	s_waitcnt lgkmcnt(1)
	v_readfirstlane_b32 s4, v1
	v_lshrrev_b32_e32 v5, 4, v12
	v_lshrrev_b32_e32 v6, 5, v12
	s_sub_i32 s4, s22, s4
	v_xor_b32_e32 v5, v5, v6
	s_ashr_i32 s5, s4, 31
	v_lshlrev_b32_e32 v5, 1, v5
	s_lshr_b32 s5, s5, 29
	v_bfe_u32 v7, v12, 5, 1
	v_and_b32_e32 v5, 2, v5
	v_and_b32_e32 v6, 3, v12
	s_add_i32 s5, s4, s5
	v_bitop3_b32 v13, v5, v6, v7 bitop3:0x36
	v_lshrrev_b32_e32 v5, 2, v12
	v_lshrrev_b32_e32 v6, 3, v12
	s_and_b32 s9, s5, 0x1fffff8
	s_lshl_b32 s5, s5, 4
	v_xor_b32_e32 v5, v5, v6
	s_sub_i32 s4, s4, s9
	s_and_b32 s9, s5, 0xffffff80
	v_lshlrev_b32_e32 v5, 1, v5
	s_waitcnt lgkmcnt(0)
	v_add_u32_e32 v0, s9, v75
	v_bfe_u32 v71, v12, 4, 2
	v_ashrrev_i32_e32 v4, 2, v12
	v_bfe_u32 v7, v12, 3, 1
	v_and_b32_e32 v5, 2, v5
	s_add_i32 s10, s8, 32
	v_ashrrev_i32_e32 v1, 31, v0
	s_lshl_b32 s4, s4, 7
	v_bitop3_b32 v14, v5, v71, v7 bitop3:0x36
	v_ashrrev_i32_e32 v5, 31, v4
	s_lshl_b64 s[0:1], s[10:11], 10
	v_lshlrev_b64 v[0:1], 11, v[0:1]
	s_ashr_i32 s5, s4, 31
	v_lshlrev_b64 v[4:5], 11, v[4:5]
	v_lshl_add_u64 v[2:3], s[80:81], 0, v[0:1]
	s_add_u32 s20, s0, s4
	v_lshl_add_u64 v[6:7], v[4:5], 0, s[12:13]
	v_lshlrev_b32_e32 v78, 4, v12
	s_addc_u32 s21, s1, s5
	v_lshl_add_u64 v[8:9], v[2:3], 0, v[6:7]
	v_lshl_add_u64 v[2:3], v[2:3], 0, v[4:5]
	v_lshlrev_b32_e32 v68, 4, v13
	v_readfirstlane_b32 s10, v78
	s_lshl_b64 s[20:21], s[20:21], 11
	v_lshl_add_u64 v[2:3], v[2:3], 0, v[68:69]
	s_mov_b32 m0, s10
	s_add_u32 s20, s38, s20
	v_add_u32_e32 v2, 0x1000, v78
	s_addc_u32 s21, s39, s21
	v_add_u32_e32 v13, 0x2000, v78
	v_readfirstlane_b32 s10, v2
	v_lshl_add_u64 v[10:11], s[20:21], 0, v[4:5]
	v_lshl_add_u64 v[8:9], v[8:9], 0, v[68:69]
	s_mov_b32 m0, s10
	v_readfirstlane_b32 s10, v13
	v_add_u32_e32 v2, 0x3000, v78
	v_lshl_add_u64 v[6:7], s[20:21], 0, v[6:7]
	v_lshl_add_u64 v[10:11], v[10:11], 0, v[68:69]
	s_mov_b32 m0, s10
	v_readfirstlane_b32 s10, v2
	v_lshl_add_u64 v[6:7], v[6:7], 0, v[68:69]
	s_mov_b32 m0, s10
	v_lshl_add_u64 v[0:1], v[4:5], 0, v[0:1]
	v_or_b32_e32 v0, v0, v68
	s_lshl_b64 s[20:21], s[4:5], 11
	v_lshl_add_u64 v[64:65], s[80:81], 0, v[0:1]
	v_lshl_add_u64 v[0:1], v[4:5], 0, s[20:21]
	v_and_b32_e32 v73, 15, v12
	v_or_b32_e32 v0, v0, v68
	v_bfe_u32 v70, v12, 6, 1
	v_ashrrev_i32_e32 v72, 7, v12
	v_lshlrev_b32_e32 v2, 6, v73
	v_lshl_add_u64 v[66:67], s[6:7], 0, v[0:1]
	v_mov_b32_e32 v0, 0
	v_lshl_or_b32 v76, v14, 4, v2
	v_lshlrev_b32_e32 v77, 12, v72
	v_lshlrev_b32_e32 v79, 12, v70
	s_mov_b32 s5, 0
	s_mov_b64 s[6:7], 0
	v_mov_b32_e32 v1, v0
	v_mov_b32_e32 v2, v0
	v_mov_b32_e32 v3, v0
	s_waitcnt vmcnt(0)
	v_mov_b32_e32 v16, v0
	v_mov_b32_e32 v17, v0
	v_mov_b32_e32 v18, v0
	v_mov_b32_e32 v19, v0
	s_waitcnt vmcnt(0)
	v_mov_b32_e32 v32, v0
	v_mov_b32_e32 v33, v0
	v_mov_b32_e32 v34, v0
	v_mov_b32_e32 v35, v0
	v_mov_b32_e32 v36, v0
	v_mov_b32_e32 v37, v0
	v_mov_b32_e32 v38, v0
	v_mov_b32_e32 v39, v0
	v_mov_b32_e32 v4, v0
	v_mov_b32_e32 v5, v0
	v_mov_b32_e32 v6, v0
	v_mov_b32_e32 v7, v0
	v_mov_b32_e32 v20, v0
	v_mov_b32_e32 v21, v0
	v_mov_b32_e32 v22, v0
	v_mov_b32_e32 v23, v0
	v_mov_b32_e32 v40, v0
	v_mov_b32_e32 v41, v0
	v_mov_b32_e32 v42, v0
	v_mov_b32_e32 v43, v0
	v_mov_b32_e32 v44, v0
	v_mov_b32_e32 v45, v0
	v_mov_b32_e32 v46, v0
	v_mov_b32_e32 v47, v0
	v_mov_b32_e32 v8, v0
	v_mov_b32_e32 v9, v0
	v_mov_b32_e32 v10, v0
	v_mov_b32_e32 v11, v0
	v_mov_b32_e32 v24, v0
	v_mov_b32_e32 v25, v0
	v_mov_b32_e32 v26, v0
	v_mov_b32_e32 v27, v0
	v_mov_b32_e32 v48, v0
	v_mov_b32_e32 v49, v0
	v_mov_b32_e32 v50, v0
	v_mov_b32_e32 v51, v0
	v_mov_b32_e32 v52, v0
	v_mov_b32_e32 v53, v0
	v_mov_b32_e32 v54, v0
	v_mov_b32_e32 v55, v0
	v_mov_b32_e32 v12, v0
	v_mov_b32_e32 v13, v0
	v_mov_b32_e32 v14, v0
	v_mov_b32_e32 v15, v0
	v_mov_b32_e32 v28, v0
	v_mov_b32_e32 v29, v0
	v_mov_b32_e32 v30, v0
	v_mov_b32_e32 v31, v0
	v_mov_b32_e32 v56, v0
	v_mov_b32_e32 v57, v0
	v_mov_b32_e32 v58, v0
	v_mov_b32_e32 v59, v0
	v_mov_b32_e32 v60, v0
	v_mov_b32_e32 v61, v0
	v_mov_b32_e32 v62, v0
	v_mov_b32_e32 v63, v0
	v_and_b32_e32 v90, 15, v122
	v_bfe_u32 v91, v122, 4, 2
	v_bfe_u32 v92, v122, 1, 3
	v_xor_b32_e32 v91, v91, v92
	v_lshlrev_b32_e32 v91, 4, v91
	v_lshl_or_b32 v76, v90, 7, v91
	v_lshlrev_b32_e32 v77, 1, v77
	v_lshlrev_b32_e32 v79, 1, v79
	v_and_b32_e32 v90, 7, v122
	v_bfe_u32 v91, v122, 4, 3
	v_xor_b32_e32 v90, v90, v91
	v_lshlrev_b32_e32 v90, 4, v90
	v_lshrrev_b32_e32 v91, 3, v122
	v_lshl_or_b32 v90, v91, 11, v90
	v_bfe_u32 v91, v122, 4, 2
	v_lshrrev_b32_e32 v92, 1, v91
	v_xor_b32_e32 v93, v91, v92
	v_and_b32_e32 v93, 1, v93
	v_lshl_or_b32 v92, v93, 1, v92
	v_and_b32_e32 v91, 3, v122
	v_xor_b32_e32 v91, v91, v92
	v_lshlrev_b32_e32 v91, 4, v91
	v_lshrrev_b32_e32 v92, 2, v122
	v_lshl_or_b32 v91, v92, 11, v91
	v_sub_u32_e32 v90, v90, v91
	v_ashrrev_i32_e32 v91, 31, v90
	v_lshl_add_u64 v[64:65], v[64:65], 0, v[90:91]
	v_lshl_add_u64 v[66:67], v[66:67], 0, v[90:91]
	s_mov_b32 s20, 0x3e00000
	s_mov_b32 s21, 0
	v_lshl_add_u64 v[66:67], v[66:67], 0, s[20:21]
; DEV unsigned pack2(float a, float b) { return (unsigned)f2bf(a) | ((unsigned)f2bf(b) << 16); }
; template <bool SWAP, class RowA, class Epi>
; DEV void gemm_tile(unsigned char* smem, RowA rowA, const bf16_t* Bt, int K, Epi epi) {
;     ...
;   for (int t = 0; t < nk; ++t) {
;     asm volatile("s_waitcnt vmcnt(0)" ::: "memory");
;     __syncthreads();
;     if (t + 1 < nk) stage(t + 1, (t + 1) & 1);
;     const unsigned char* SA = smem + (t & 1) * 16384;
;     const unsigned char* SB = SA + 8192;
;     bf16x8 At[4], Bl[4];
; #pragma unroll
;     for (int m = 0; m < 4; ++m) At[m] = *reinterpret_cast<const bf16x8*>(SA + (wr * 64 + m * 16) * 64 + rdoff);
; #pragma unroll
;     for (int n = 0; n < 4; ++n) Bl[n] = *reinterpret_cast<const bf16x8*>(SB + (wc * 64 + n * 16) * 64 + rdoff);
; #pragma unroll
;     for (int m = 0; m < 4; ++m)
; #pragma unroll
;       for (int n = 0; n < 4; ++n)
;         acc[m][n] = SWAP ? __builtin_amdgcn_mfma_f32_16x16x32_bf16(Bl[n], At[m], acc[m][n], 0, 0, 0)
;                          : __builtin_amdgcn_mfma_f32_16x16x32_bf16(At[m], Bl[n], acc[m][n], 0, 0, 0);
;   }
; DEV void phase_moe2(const Params& p, int l, unsigned char* smem) {
;     ...
; #pragma unroll
;         for (int n = 0; n < 4; ++n) {
;           const int col = nt * 128 + wc * 64 + n * 16 + fq * 4;
;           const float4 b4 = *reinterpret_cast<const float4*>(bd + col);
; #pragma unroll
;           for (int m = 0; m < 4; ++m) {
;             const int i = mt * 128 + wr * 64 + m * 16 + fr;
;             if (i < cnt) {
;               const float g = gl[i];
;               *reinterpret_cast<uint2*>(p.out2 + (size_t)(rowoff + i) * 1024 + col) =
;                   make_uint2(pack2((acc[m][n][0] + b4.x) * g, (acc[m][n][1] + b4.y) * g), pack2((acc[m][n][2] + b4.z) * g, (acc[m][n][3] + b4.w) * g));
;             }
.LBB0_2411:
	s_bitcmp1_b32 s6, 6
	s_cbranch_scc1 .Lpair_odd_2411
	s_waitcnt lgkmcnt(0)
	s_barrier
	v_readfirstlane_b32 s20, v78
	s_mov_b32 m0, s20
	v_lshl_add_u64 v[90:91], v[64:65], 0, s[6:7]
	s_mov_b64 s[20:21], 0x10000
	global_load_lds_dwordx4 v[90:91], off
	s_add_i32 m0, m0, 0x1000
	v_lshl_add_u64 v[92:93], v[90:91], 0, s[20:21]
	global_load_lds_dwordx4 v[92:93], off
	s_add_i32 m0, m0, 0x1000
	v_lshl_add_u64 v[90:91], v[92:93], 0, s[20:21]
	global_load_lds_dwordx4 v[90:91], off
	s_add_i32 m0, m0, 0x1000
	v_lshl_add_u64 v[92:93], v[90:91], 0, s[20:21]
	global_load_lds_dwordx4 v[92:93], off
	s_add_i32 m0, m0, 0x1000
	v_lshl_add_u64 v[90:91], v[66:67], 0, s[6:7]
	global_load_lds_dwordx4 v[90:91], off
	s_add_i32 m0, m0, 0x1000
	v_lshl_add_u64 v[92:93], v[90:91], 0, s[20:21]
	global_load_lds_dwordx4 v[92:93], off
	s_add_i32 m0, m0, 0x1000
	v_lshl_add_u64 v[90:91], v[92:93], 0, s[20:21]
	global_load_lds_dwordx4 v[90:91], off
	s_add_i32 m0, m0, 0x1000
	v_lshl_add_u64 v[92:93], v[90:91], 0, s[20:21]
	global_load_lds_dwordx4 v[92:93], off
	s_waitcnt vmcnt(0)
	s_barrier
.Lpair_odd_2411:
	s_and_b32 s5, s6, 64
	v_xor_b32_e32 v68, s5, v76
	v_add_u32_e32 v89, v68, v77
	v_add_u32_e32 v68, v68, v79
	ds_read_b128 v[90:93], v68 offset:16384
	ds_read_b128 v[94:97], v68 offset:18432
	ds_read_b128 v[98:101], v89
	ds_read_b128 v[102:105], v89 offset:2048
	ds_read_b128 v[106:109], v68 offset:20480
	ds_read_b128 v[110:113], v68 offset:22528
	s_waitcnt lgkmcnt(0)
	v_mfma_f32_16x16x32_bf16 v[60:63], v[90:93], v[98:101], v[60:63]
	s_add_u32 s6, s6, 64
	s_addc_u32 s7, s7, 0
	s_cmpk_eq_i32 s6, 0x7c0
	v_mfma_f32_16x16x32_bf16 v[56:59], v[94:97], v[98:101], v[56:59]
	v_mfma_f32_16x16x32_bf16 v[28:31], v[106:109], v[98:101], v[28:31]
	v_mfma_f32_16x16x32_bf16 v[12:15], v[110:113], v[98:101], v[12:15]
	v_mfma_f32_16x16x32_bf16 v[52:55], v[90:93], v[102:105], v[52:55]
	v_mfma_f32_16x16x32_bf16 v[48:51], v[94:97], v[102:105], v[48:51]
	v_mfma_f32_16x16x32_bf16 v[24:27], v[106:109], v[102:105], v[24:27]
	v_mfma_f32_16x16x32_bf16 v[8:11], v[110:113], v[102:105], v[8:11]
	ds_read_b128 v[98:101], v89 offset:4096
	ds_read_b128 v[102:105], v89 offset:6144
	s_waitcnt lgkmcnt(0)
	v_mfma_f32_16x16x32_bf16 v[44:47], v[90:93], v[98:101], v[44:47]
	v_mfma_f32_16x16x32_bf16 v[40:43], v[94:97], v[98:101], v[40:43]
	v_mfma_f32_16x16x32_bf16 v[20:23], v[106:109], v[98:101], v[20:23]
	v_mfma_f32_16x16x32_bf16 v[4:7], v[110:113], v[98:101], v[4:7]
	v_mfma_f32_16x16x32_bf16 v[36:39], v[90:93], v[102:105], v[36:39]
	v_mfma_f32_16x16x32_bf16 v[32:35], v[94:97], v[102:105], v[32:35]
	v_mfma_f32_16x16x32_bf16 v[16:19], v[106:109], v[102:105], v[16:19]
	v_mfma_f32_16x16x32_bf16 v[0:3], v[110:113], v[102:105], v[0:3]
	s_cbranch_scc0 .LBB0_2411
	v_xor_b32_e32 v89, 64, v76
	v_add_u32_e32 v68, v89, v79
	s_waitcnt vmcnt(0)
	s_waitcnt vmcnt(0)
	s_barrier
	ds_read_b128 v[90:93], v68 offset:16384
	ds_read_b128 v[94:97], v68 offset:18432
	ds_read_b128 v[98:101], v68 offset:20480
	ds_read_b128 v[102:105], v68 offset:22528
	v_add_u32_e32 v89, v89, v77
	ds_read_b128 v[76:79], v89
	ds_read_b128 v[106:109], v89 offset:4096
	s_waitcnt lgkmcnt(1)
	v_mfma_f32_16x16x32_bf16 v[64:67], v[90:93], v[76:79], v[60:63]
	s_lshl_b64 s[0:1], s[0:1], 2
	s_add_u32 s0, s44, s0
	s_addc_u32 s1, s45, s1
	v_mfma_f32_16x16x32_bf16 v[56:59], v[94:97], v[76:79], v[56:59]
	s_mul_i32 s10, s8, 0x4200
	v_lshl_add_u32 v68, v72, 6, s9
	v_or_b32_e32 v72, v68, v73
	v_mfma_f32_16x16x32_bf16 v[28:31], v[98:101], v[76:79], v[28:31]
	v_cmp_lt_i32_e32 vcc, v72, v74
	v_ashrrev_i32_e32 v73, 31, v72
	v_mfma_f32_16x16x32_bf16 v[12:15], v[102:105], v[76:79], v[12:15]
	ds_read_b128 v[76:79], v89 offset:2048
	s_waitcnt lgkmcnt(0)
	v_mfma_f32_16x16x32_bf16 v[60:63], v[90:93], v[76:79], v[52:55]
	v_mfma_f32_16x16x32_bf16 v[52:55], v[90:93], v[106:109], v[44:47]
	s_nop 2
	v_lshlrev_b32_e32 v44, 6, v70
	v_lshlrev_b32_e32 v45, 2, v71
	v_or3_b32 v70, v44, v45, s4
	v_ashrrev_i32_e32 v71, 31, v70
	v_mfma_f32_16x16x32_bf16 v[48:51], v[94:97], v[76:79], v[48:51]
	v_mfma_f32_16x16x32_bf16 v[24:27], v[98:101], v[76:79], v[24:27]
	v_mfma_f32_16x16x32_bf16 v[8:11], v[102:105], v[76:79], v[8:11]
	v_lshl_add_u64 v[76:77], v[70:71], 2, s[0:1]
	global_load_dwordx4 v[44:47], v[76:77], off
	s_lshl_b64 s[0:1], s[10:11], 2
	v_mfma_f32_16x16x32_bf16 v[40:43], v[94:97], v[106:109], v[40:43]
	s_add_u32 s4, s78, s0
	v_add_u32_e32 v78, v72, v75
	s_addc_u32 s5, s79, s1
	v_mfma_f32_16x16x32_bf16 v[20:23], v[98:101], v[106:109], v[20:23]
	v_ashrrev_i32_e32 v79, 31, v78
	v_mfma_f32_16x16x32_bf16 v[4:7], v[102:105], v[106:109], v[4:7]
	ds_read_b128 v[106:109], v89 offset:6144
	s_waitcnt lgkmcnt(0)
	v_mfma_f32_16x16x32_bf16 v[36:39], v[90:93], v[106:109], v[36:39]
	v_mfma_f32_16x16x32_bf16 v[32:35], v[94:97], v[106:109], v[32:35]
	v_mfma_f32_16x16x32_bf16 v[16:19], v[98:101], v[106:109], v[16:19]
	v_mfma_f32_16x16x32_bf16 v[0:3], v[102:105], v[106:109], v[0:3]
	v_lshl_add_u64 v[124:125], v[72:73], 2, s[4:5]
	global_load_dword v126, v[124:125], off
	global_load_dword v127, v[124:125], off offset:64
	global_load_dword v128, v[124:125], off offset:128
	global_load_dword v129, v[124:125], off offset:192
	global_load_dwordx4 v[130:133], v[76:77], off offset:64
	global_load_dwordx4 v[134:137], v[76:77], off offset:128
	global_load_dwordx4 v[138:141], v[76:77], off offset:192
	s_waitcnt vmcnt(0)
	s_and_saveexec_b64 s[0:1], vcc
	s_cbranch_execz .LBB0_2414
	v_lshl_add_u64 v[90:91], v[72:73], 2, s[4:5]
	v_mov_b32_e32 v68, v126
	v_pk_add_f32 v[66:67], v[66:67], v[46:47]
	v_pk_add_f32 v[64:65], v[64:65], v[44:45]
	v_lshlrev_b64 v[90:91], 11, v[78:79]
	v_mov_b32_e32 v93, v66
	v_mov_b32_e32 v66, v65
	v_lshl_add_u64 v[90:91], s[82:83], 0, v[90:91]
	v_mov_b32_e32 v92, v64
	v_lshl_add_u64 v[64:65], v[70:71], 1, v[90:91]
	v_pk_mul_f32 v[66:67], v[66:67], v[68:69] op_sel_hi:[1,0]
	v_pk_mul_f32 v[90:91], v[92:93], v[68:69] op_sel_hi:[1,0]
	v_and_b32_sdwa v92, v67, v87 dst_sel:DWORD dst_unused:UNUSED_PAD src0_sel:WORD_1 src1_sel:DWORD
	v_and_b32_sdwa v93, v66, v87 dst_sel:DWORD dst_unused:UNUSED_PAD src0_sel:WORD_1 src1_sel:DWORD
	v_and_b32_sdwa v68, v91, v87 dst_sel:DWORD dst_unused:UNUSED_PAD src0_sel:WORD_1 src1_sel:DWORD
	v_and_b32_sdwa v89, v90, v87 dst_sel:DWORD dst_unused:UNUSED_PAD src0_sel:WORD_1 src1_sel:DWORD
	v_add3_u32 v67, v67, v92, s2
	v_add3_u32 v66, v66, v93, s2
	v_add3_u32 v89, v90, v89, s2
	v_add3_u32 v68, v91, v68, s2
	v_and_b32_e32 v67, 0xffff0000, v67
	v_and_b32_e32 v66, 0xffff0000, v66
	v_or_b32_sdwa v67, v67, v68 dst_sel:DWORD dst_unused:UNUSED_PAD src0_sel:DWORD src1_sel:WORD_1
	v_or_b32_sdwa v66, v66, v89 dst_sel:DWORD dst_unused:UNUSED_PAD src0_sel:DWORD src1_sel:WORD_1
	global_store_dwordx2 v[64:65], v[66:67], off
